# scan: XCD-affine task map so the 4 row-quarter workgroups of a (seq,head) share an L2; plus hand-scheduled scan body
# speedup vs baseline: 1.0077x; 1.0077x over previous
; #define LAS __attribute__((address_space(3)))
; __device__ __forceinline__ float bf_lo(unsigned w) { return __uint_as_float(w << 16); }
; __device__ __forceinline__ void rwkv_scan(const Params& p, LAS unsigned char* lds, int rowbase, int T, int h, int q4, const float* S0, float* Sout) {
;     const int tid = opaque_tid(), lane = tid & 63, w = __builtin_amdgcn_readfirstlane(tid >> 6), rowl = lane >> 4, seg = lane & 15; const int vloc = (w & 3) * 4 + rowl, vrow = q4 * 16 + vloc;
;     unsigned char* ws = p.ws;
;     const float* decay = p.out; const bf16_t* kk = (const bf16_t*)((const unsigned char*)p.out + 68157440); const bf16_t* kka = (const bf16_t*)((const unsigned char*)p.out + 68157440 + HALF512);
;     const bf16_t* kp = (const bf16_t*)(ws + WS_PRW); const bf16_t* rb = (const bf16_t*)(ws + WS_A); const bf16_t* vb = (const bf16_t*)(ws + WS_A + HALF512);
;     bf16_t* ob = (bf16_t*)(ws + WS_B);
;     const bool comp = w < 4;
;     f32x4 S = (f32x4){0.f, 0.f, 0.f, 0.f};
;     if (comp && S0) S = *(const f32x4*)(S0 + vrow * 64 + seg * 4);
;     constexpr int BUF = 43008;
;     const bool ldr = w >= 4; const int lt = tid & 255, lstep = lt >> 4, lj = lt & 15;
;     f32x4 gd[2]; u32x2 gk[2], ga[2], gp[2], gr[2], gv[2];
;     auto gload = [&](int c) {
;         if (ldr) {
; #pragma unroll
;             for (int q = 0; q < 2; ++q) {
;                 const size_t row = (size_t)(rowbase + c * 32 + lstep + q * 16); const size_t o = row * 512 + h * 64 + lj * 4;
;                 gd[q] = *(const f32x4*)(decay + o); gk[q] = *(const u32x2*)(kk + o); ga[q] = *(const u32x2*)(kka + o); gp[q] = *(const u32x2*)(kp + o); gr[q] = *(const u32x2*)(rb + o);
;                 gv[q] = *(const u32x2*)(vb + row * 512 + h * 64 + q4 * 16 + (lj & 3) * 4);
;             }
;         }
;     };
;     auto up4 = [](const u32x2 x) { return (f32x4){bf_lo(x.x), bf_hi(x.x), bf_lo(x.y), bf_hi(x.y)}; };
;     float selv[16];
; #pragma unroll
;     for (int i = 0; i < 16; ++i) selv[i] = (seg == i) ? 1.0f : 0.0f;
;     const int nch = T / 32;
;     gload(0);
; __device__ __forceinline__ void ph_scan(const Params& p, LAS unsigned char* lds) {
;     ...
;     for (int task = blockIdx.x; task < 768; task += gridDim.x) {
;         if (task < 256) { const int b = task >> 5, h = (task >> 2) & 7, q4 = task & 3; rwkv_scan(p, lds, b * 4096, 4096, h, q4, nullptr, p.out + O_PRW + (size_t)(b * 8 + h) * 4096); }
.LBB0_757:
	s_and_b32 s47, s44, 7
	s_lshr_b32 s5, s44, 3
	s_lshl_b32 s47, s47, 3
	s_lshr_b32 s4, s5, 2
	s_add_i32 s47, s47, s4
	s_lshl_b32 s47, s47, 2
	s_and_b32 s5, s5, 3
	s_or_b32 s47, s47, s5
	s_bfe_u32 s45, s47, 0x30002
	v_mov_b32_e32 v14, v200
	s_ashr_i32 s33, s47, 5
	v_readfirstlane_b32 s4, v14
	s_ashr_i32 s46, s4, 6
	s_lshl_b32 s4, s47, 4
	s_lshl_b32 s42, s33, 12
	s_and_b32 s43, s4, 48
	s_cmp_lt_i32 s46, 4
	s_cselect_b64 s[30:31], -1, 0
	s_cmp_gt_i32 s46, 3
	s_waitcnt vmcnt(0)
	v_and_b32_e32 v12, 15, v14
	s_cselect_b64 s[38:39], -1, 0
	v_bfe_u32 v13, v14, 4, 4
	s_and_b64 vcc, exec, s[38:39]
	v_lshlrev_b32_e32 v15, 2, v12
	s_cbranch_vccz .LBB0_759
	v_or_b32_e32 v8, s42, v13
	v_ashrrev_i32_e32 v9, 31, v8
	s_lshl_b32 s22, s45, 6
	v_lshlrev_b32_e32 v16, 2, v12
	v_lshlrev_b64 v[2:3], 9, v[8:9]
	v_or_b32_e32 v0, s22, v16
	v_or_b32_e32 v2, v2, v0
	v_lshl_add_u64 v[4:5], v[2:3], 2, s[90:91]
	v_lshlrev_b64 v[2:3], 1, v[2:3]
	v_lshl_add_u64 v[10:11], s[6:7], 0, v[2:3]
	global_load_dwordx4 v[4:7], v[4:5], off
	s_nop 0
	global_load_dwordx2 v[18:19], v[10:11], off
	v_lshl_add_u64 v[10:11], s[8:9], 0, v[2:3]
	global_load_dwordx2 v[20:21], v[10:11], off
	v_lshl_add_u64 v[10:11], s[10:11], 0, v[2:3]
	v_lshl_add_u64 v[24:25], s[12:13], 0, v[2:3]
	v_lshlrev_b64 v[2:3], 10, v[8:9]
	v_lshl_add_u64 v[2:3], s[16:17], 0, v[2:3]
	s_lshl_b32 s4, s45, 7
	s_mov_b32 s5, s23
	v_or_b32_e32 v34, 16, v8
	v_lshl_add_u64 v[2:3], v[2:3], 0, s[4:5]
	s_lshl_b32 s50, s43, 1
	s_mov_b32 s51, s23
	v_ashrrev_i32_e32 v35, 31, v34
	v_lshl_add_u64 v[22:23], v[2:3], 0, s[50:51]
	v_and_b32_e32 v2, 12, v16
	v_lshlrev_b64 v[8:9], 9, v[34:35]
	v_lshlrev_b64 v[34:35], 10, v[34:35]
	v_lshlrev_b32_e32 v28, 1, v2
	v_mov_b32_e32 v29, v1
	v_or_b32_e32 v8, v8, v0
	v_lshl_add_u64 v[34:35], s[16:17], 0, v[34:35]
	v_lshl_add_u64 v[26:27], v[22:23], 0, v[28:29]
	v_lshlrev_b64 v[36:37], 1, v[8:9]
	v_lshl_add_u64 v[34:35], v[34:35], 0, s[4:5]
	global_load_dwordx2 v[22:23], v[10:11], off
	s_nop 0
	global_load_dwordx2 v[24:25], v[24:25], off
	s_nop 0
	global_load_dwordx2 v[26:27], v[26:27], off
	v_lshl_add_u64 v[10:11], v[8:9], 2, s[90:91]
	v_lshl_add_u64 v[30:31], s[6:7], 0, v[36:37]
	v_lshl_add_u64 v[32:33], s[8:9], 0, v[36:37]
	v_lshl_add_u64 v[38:39], s[10:11], 0, v[36:37]
	v_lshl_add_u64 v[36:37], s[12:13], 0, v[36:37]
	v_lshl_add_u64 v[34:35], v[34:35], 0, s[50:51]
	global_load_dwordx4 v[8:11], v[10:11], off
	s_nop 0
	global_load_dwordx2 v[30:31], v[30:31], off
	v_lshl_add_u64 v[28:29], v[34:35], 0, v[28:29]
	global_load_dwordx2 v[32:33], v[32:33], off
	s_nop 0
	global_load_dwordx2 v[34:35], v[38:39], off
	s_nop 0
	global_load_dwordx2 v[36:37], v[36:37], off
	s_nop 0
	global_load_dwordx2 v[38:39], v[28:29], off
	v_mov_b32_e32 v3, v1
	v_mov_b64_e32 v[28:29], v[0:1]
	s_cbranch_execz .LBB0_760
	s_branch .LBB0_761
